# final RMSNorm phase hand-pipelined: gain resident in registers, next row prefetched, one wait per row, dwordx4 stores batched
# baseline (speedup 1.0000x reference)
.LBB0_2696:
	s_or_b64 exec, exec, s[0:1]
	s_waitcnt lgkmcnt(0)
	s_barrier
	s_and_saveexec_b64 s[0:1], s[78:79]
	s_cbranch_execz .LBB0_2699
	v_mbcnt_lo_u32_b32 v80, -1, 0
	v_mbcnt_hi_u32_b32 v80, -1, v80
	v_lshlrev_b32_e32 v96, 4, v80
	v_xor_b32_e32 v98, 32, v80
	v_lshlrev_b32_e32 v98, 2, v98
	v_xor_b32_e32 v99, 16, v80
	v_lshlrev_b32_e32 v99, 2, v99
	v_xor_b32_e32 v100, 8, v80
	v_lshlrev_b32_e32 v100, 2, v100
	v_xor_b32_e32 v101, 4, v80
	v_lshlrev_b32_e32 v101, 2, v101
	v_xor_b32_e32 v102, 2, v80
	v_lshlrev_b32_e32 v102, 2, v102
	v_xor_b32_e32 v103, 1, v80
	v_lshlrev_b32_e32 v103, 2, v103
	v_mov_b32_e32 v104, 0x358637bd
	v_mov_b32_e32 v107, 0
	global_load_dwordx4 v[32:35], v96, s[26:27] offset:0
	global_load_dwordx4 v[36:39], v96, s[26:27] offset:1024
	global_load_dwordx4 v[40:43], v96, s[26:27] offset:2048
	global_load_dwordx4 v[44:47], v96, s[26:27] offset:3072
	v_readfirstlane_b32 s98, v148
	s_nop 3
	s_lshl_b32 s99, s98, 12
	s_add_u32 s100, s88, s99
	s_addc_u32 s101, s89, 0
	global_load_dwordx4 v[0:3], v96, s[100:101] offset:0
	global_load_dwordx4 v[4:7], v96, s[100:101] offset:1024
	global_load_dwordx4 v[8:11], v96, s[100:101] offset:2048
	global_load_dwordx4 v[12:15], v96, s[100:101] offset:3072
	s_add_u32 s98, s98, 0x800
	s_lshl_b32 s99, s98, 12
	s_add_u32 s100, s88, s99
	s_addc_u32 s101, s89, 0
	global_load_dwordx4 v[16:19], v96, s[100:101] offset:0
	global_load_dwordx4 v[20:23], v96, s[100:101] offset:1024
	global_load_dwordx4 v[24:27], v96, s[100:101] offset:2048
	global_load_dwordx4 v[28:31], v96, s[100:101] offset:3072
	s_sub_u32 s98, s98, 0x800
	s_waitcnt vmcnt(4)
	v_mul_f32_e32 v80, v1, v1
	v_mul_f32_e32 v81, v5, v5
	v_mul_f32_e32 v82, v9, v9
	v_mul_f32_e32 v83, v13, v13
	v_fmac_f32_e32 v80, v0, v0
	v_fmac_f32_e32 v81, v4, v4
	v_fmac_f32_e32 v82, v8, v8
	v_fmac_f32_e32 v83, v12, v12
	v_fmac_f32_e32 v80, v2, v2
	v_fmac_f32_e32 v81, v6, v6
	v_fmac_f32_e32 v82, v10, v10
	v_fmac_f32_e32 v83, v14, v14
	v_fmac_f32_e32 v80, v3, v3
	v_fmac_f32_e32 v81, v7, v7
	v_fmac_f32_e32 v82, v11, v11
	v_fmac_f32_e32 v83, v15, v15
	v_add_f32_e32 v84, v80, v81
	v_add_f32_e32 v84, v84, v82
	v_add_f32_e32 v84, v84, v83
	ds_bpermute_b32 v85, v98, v84
	s_waitcnt lgkmcnt(0)
	v_add_f32_e32 v84, v84, v85
	ds_bpermute_b32 v85, v99, v84
	s_waitcnt lgkmcnt(0)
	v_add_f32_e32 v84, v84, v85
	ds_bpermute_b32 v85, v100, v84
	s_waitcnt lgkmcnt(0)
	v_add_f32_e32 v84, v84, v85
	ds_bpermute_b32 v85, v101, v84
	s_waitcnt lgkmcnt(0)
	v_add_f32_e32 v84, v84, v85
	ds_bpermute_b32 v85, v102, v84
	s_waitcnt lgkmcnt(0)
	v_add_f32_e32 v84, v84, v85
	ds_bpermute_b32 v85, v103, v84
	s_waitcnt lgkmcnt(0)
	v_add_f32_e32 v84, v84, v85
	v_fmamk_f32 v84, v84, 0x3a800000, v104
	v_mul_f32_e32 v85, 0x4b800000, v84
	v_cmp_gt_f32_e32 vcc, 0x800000, v84
	s_nop 1
	v_cndmask_b32_e32 v84, v84, v85, vcc
	v_rsq_f32_e32 v84, v84
	s_nop 0
	v_mul_f32_e32 v85, 0x45800000, v84
	v_cndmask_b32_e32 v106, v84, v85, vcc
	s_lshl_b32 s99, s98, 12
	s_add_u32 s100, s88, s99
	s_addc_u32 s101, s89, 0
	v_pk_mul_f32 v[0:1], v[0:1], v[106:107] op_sel_hi:[1,0]
	v_pk_mul_f32 v[2:3], v[2:3], v[106:107] op_sel_hi:[1,0]
	v_pk_mul_f32 v[0:1], v[32:33], v[0:1]
	v_pk_mul_f32 v[2:3], v[34:35], v[2:3]
	global_store_dwordx4 v96, v[0:3], s[100:101] offset:0
	v_pk_mul_f32 v[4:5], v[4:5], v[106:107] op_sel_hi:[1,0]
	v_pk_mul_f32 v[6:7], v[6:7], v[106:107] op_sel_hi:[1,0]
	v_pk_mul_f32 v[4:5], v[36:37], v[4:5]
	v_pk_mul_f32 v[6:7], v[38:39], v[6:7]
	global_store_dwordx4 v96, v[4:7], s[100:101] offset:1024
	v_pk_mul_f32 v[8:9], v[8:9], v[106:107] op_sel_hi:[1,0]
	v_pk_mul_f32 v[10:11], v[10:11], v[106:107] op_sel_hi:[1,0]
	v_pk_mul_f32 v[8:9], v[40:41], v[8:9]
	v_pk_mul_f32 v[10:11], v[42:43], v[10:11]
	global_store_dwordx4 v96, v[8:11], s[100:101] offset:2048
	v_pk_mul_f32 v[12:13], v[12:13], v[106:107] op_sel_hi:[1,0]
	v_pk_mul_f32 v[14:15], v[14:15], v[106:107] op_sel_hi:[1,0]
	v_pk_mul_f32 v[12:13], v[44:45], v[12:13]
	v_pk_mul_f32 v[14:15], v[46:47], v[14:15]
	global_store_dwordx4 v96, v[12:15], s[100:101] offset:3072
	s_add_u32 s98, s98, 0x800
	s_add_u32 s98, s98, 0x800
	s_lshl_b32 s99, s98, 12
	s_add_u32 s100, s88, s99
	s_addc_u32 s101, s89, 0
	global_load_dwordx4 v[0:3], v96, s[100:101] offset:0
	global_load_dwordx4 v[4:7], v96, s[100:101] offset:1024
	global_load_dwordx4 v[8:11], v96, s[100:101] offset:2048
	global_load_dwordx4 v[12:15], v96, s[100:101] offset:3072
	s_sub_u32 s98, s98, 0x800
	s_waitcnt vmcnt(8)
	v_mul_f32_e32 v80, v17, v17
	v_mul_f32_e32 v81, v21, v21
	v_mul_f32_e32 v82, v25, v25
	v_mul_f32_e32 v83, v29, v29
	v_fmac_f32_e32 v80, v16, v16
	v_fmac_f32_e32 v81, v20, v20
	v_fmac_f32_e32 v82, v24, v24
	v_fmac_f32_e32 v83, v28, v28
	v_fmac_f32_e32 v80, v18, v18
	v_fmac_f32_e32 v81, v22, v22
	v_fmac_f32_e32 v82, v26, v26
	v_fmac_f32_e32 v83, v30, v30
	v_fmac_f32_e32 v80, v19, v19
	v_fmac_f32_e32 v81, v23, v23
	v_fmac_f32_e32 v82, v27, v27
	v_fmac_f32_e32 v83, v31, v31
	v_add_f32_e32 v84, v80, v81
	v_add_f32_e32 v84, v84, v82
	v_add_f32_e32 v84, v84, v83
	ds_bpermute_b32 v85, v98, v84
	s_waitcnt lgkmcnt(0)
	v_add_f32_e32 v84, v84, v85
	ds_bpermute_b32 v85, v99, v84
	s_waitcnt lgkmcnt(0)
	v_add_f32_e32 v84, v84, v85
	ds_bpermute_b32 v85, v100, v84
	s_waitcnt lgkmcnt(0)
	v_add_f32_e32 v84, v84, v85
	ds_bpermute_b32 v85, v101, v84
	s_waitcnt lgkmcnt(0)
	v_add_f32_e32 v84, v84, v85
	ds_bpermute_b32 v85, v102, v84
	s_waitcnt lgkmcnt(0)
	v_add_f32_e32 v84, v84, v85
	ds_bpermute_b32 v85, v103, v84
	s_waitcnt lgkmcnt(0)
	v_add_f32_e32 v84, v84, v85
	v_fmamk_f32 v84, v84, 0x3a800000, v104
	v_mul_f32_e32 v85, 0x4b800000, v84
	v_cmp_gt_f32_e32 vcc, 0x800000, v84
	s_nop 1
	v_cndmask_b32_e32 v84, v84, v85, vcc
	v_rsq_f32_e32 v84, v84
	s_nop 0
	v_mul_f32_e32 v85, 0x45800000, v84
	v_cndmask_b32_e32 v106, v84, v85, vcc
	s_lshl_b32 s99, s98, 12
	s_add_u32 s100, s88, s99
	s_addc_u32 s101, s89, 0
	v_pk_mul_f32 v[16:17], v[16:17], v[106:107] op_sel_hi:[1,0]
	v_pk_mul_f32 v[18:19], v[18:19], v[106:107] op_sel_hi:[1,0]
	v_pk_mul_f32 v[16:17], v[32:33], v[16:17]
	v_pk_mul_f32 v[18:19], v[34:35], v[18:19]
	global_store_dwordx4 v96, v[16:19], s[100:101] offset:0
	v_pk_mul_f32 v[20:21], v[20:21], v[106:107] op_sel_hi:[1,0]
	v_pk_mul_f32 v[22:23], v[22:23], v[106:107] op_sel_hi:[1,0]
	v_pk_mul_f32 v[20:21], v[36:37], v[20:21]
	v_pk_mul_f32 v[22:23], v[38:39], v[22:23]
	global_store_dwordx4 v96, v[20:23], s[100:101] offset:1024
	v_pk_mul_f32 v[24:25], v[24:25], v[106:107] op_sel_hi:[1,0]
	v_pk_mul_f32 v[26:27], v[26:27], v[106:107] op_sel_hi:[1,0]
	v_pk_mul_f32 v[24:25], v[40:41], v[24:25]
	v_pk_mul_f32 v[26:27], v[42:43], v[26:27]
	global_store_dwordx4 v96, v[24:27], s[100:101] offset:2048
	v_pk_mul_f32 v[28:29], v[28:29], v[106:107] op_sel_hi:[1,0]
	v_pk_mul_f32 v[30:31], v[30:31], v[106:107] op_sel_hi:[1,0]
	v_pk_mul_f32 v[28:29], v[44:45], v[28:29]
	v_pk_mul_f32 v[30:31], v[46:47], v[30:31]
	global_store_dwordx4 v96, v[28:31], s[100:101] offset:3072
	s_add_u32 s98, s98, 0x800
	s_add_u32 s98, s98, 0x800
	s_lshl_b32 s99, s98, 12
	s_add_u32 s100, s88, s99
	s_addc_u32 s101, s89, 0
	global_load_dwordx4 v[16:19], v96, s[100:101] offset:0
	global_load_dwordx4 v[20:23], v96, s[100:101] offset:1024
	global_load_dwordx4 v[24:27], v96, s[100:101] offset:2048
	global_load_dwordx4 v[28:31], v96, s[100:101] offset:3072
	s_sub_u32 s98, s98, 0x800
	s_waitcnt vmcnt(8)
	v_mul_f32_e32 v80, v1, v1
	v_mul_f32_e32 v81, v5, v5
	v_mul_f32_e32 v82, v9, v9
	v_mul_f32_e32 v83, v13, v13
	v_fmac_f32_e32 v80, v0, v0
	v_fmac_f32_e32 v81, v4, v4
	v_fmac_f32_e32 v82, v8, v8
	v_fmac_f32_e32 v83, v12, v12
	v_fmac_f32_e32 v80, v2, v2
	v_fmac_f32_e32 v81, v6, v6
	v_fmac_f32_e32 v82, v10, v10
	v_fmac_f32_e32 v83, v14, v14
	v_fmac_f32_e32 v80, v3, v3
	v_fmac_f32_e32 v81, v7, v7
	v_fmac_f32_e32 v82, v11, v11
	v_fmac_f32_e32 v83, v15, v15
	v_add_f32_e32 v84, v80, v81
	v_add_f32_e32 v84, v84, v82
	v_add_f32_e32 v84, v84, v83
	ds_bpermute_b32 v85, v98, v84
	s_waitcnt lgkmcnt(0)
	v_add_f32_e32 v84, v84, v85
	ds_bpermute_b32 v85, v99, v84
	s_waitcnt lgkmcnt(0)
	v_add_f32_e32 v84, v84, v85
	ds_bpermute_b32 v85, v100, v84
	s_waitcnt lgkmcnt(0)
	v_add_f32_e32 v84, v84, v85
	ds_bpermute_b32 v85, v101, v84
	s_waitcnt lgkmcnt(0)
	v_add_f32_e32 v84, v84, v85
	ds_bpermute_b32 v85, v102, v84
	s_waitcnt lgkmcnt(0)
	v_add_f32_e32 v84, v84, v85
	ds_bpermute_b32 v85, v103, v84
	s_waitcnt lgkmcnt(0)
	v_add_f32_e32 v84, v84, v85
	v_fmamk_f32 v84, v84, 0x3a800000, v104
	v_mul_f32_e32 v85, 0x4b800000, v84
	v_cmp_gt_f32_e32 vcc, 0x800000, v84
	s_nop 1
	v_cndmask_b32_e32 v84, v84, v85, vcc
	v_rsq_f32_e32 v84, v84
	s_nop 0
	v_mul_f32_e32 v85, 0x45800000, v84
	v_cndmask_b32_e32 v106, v84, v85, vcc
	s_lshl_b32 s99, s98, 12
	s_add_u32 s100, s88, s99
	s_addc_u32 s101, s89, 0
	v_pk_mul_f32 v[0:1], v[0:1], v[106:107] op_sel_hi:[1,0]
	v_pk_mul_f32 v[2:3], v[2:3], v[106:107] op_sel_hi:[1,0]
	v_pk_mul_f32 v[0:1], v[32:33], v[0:1]
	v_pk_mul_f32 v[2:3], v[34:35], v[2:3]
	global_store_dwordx4 v96, v[0:3], s[100:101] offset:0
	v_pk_mul_f32 v[4:5], v[4:5], v[106:107] op_sel_hi:[1,0]
	v_pk_mul_f32 v[6:7], v[6:7], v[106:107] op_sel_hi:[1,0]
	v_pk_mul_f32 v[4:5], v[36:37], v[4:5]
	v_pk_mul_f32 v[6:7], v[38:39], v[6:7]
	global_store_dwordx4 v96, v[4:7], s[100:101] offset:1024
	v_pk_mul_f32 v[8:9], v[8:9], v[106:107] op_sel_hi:[1,0]
	v_pk_mul_f32 v[10:11], v[10:11], v[106:107] op_sel_hi:[1,0]
	v_pk_mul_f32 v[8:9], v[40:41], v[8:9]
	v_pk_mul_f32 v[10:11], v[42:43], v[10:11]
	global_store_dwordx4 v96, v[8:11], s[100:101] offset:2048
	v_pk_mul_f32 v[12:13], v[12:13], v[106:107] op_sel_hi:[1,0]
	v_pk_mul_f32 v[14:15], v[14:15], v[106:107] op_sel_hi:[1,0]
	v_pk_mul_f32 v[12:13], v[44:45], v[12:13]
	v_pk_mul_f32 v[14:15], v[46:47], v[14:15]
	global_store_dwordx4 v96, v[12:15], s[100:101] offset:3072
	s_add_u32 s98, s98, 0x800
	s_add_u32 s98, s98, 0x800
	s_lshl_b32 s99, s98, 12
	s_add_u32 s100, s88, s99
	s_addc_u32 s101, s89, 0
	global_load_dwordx4 v[0:3], v96, s[100:101] offset:0
	global_load_dwordx4 v[4:7], v96, s[100:101] offset:1024
	global_load_dwordx4 v[8:11], v96, s[100:101] offset:2048
	global_load_dwordx4 v[12:15], v96, s[100:101] offset:3072
	s_sub_u32 s98, s98, 0x800
	s_waitcnt vmcnt(8)
	v_mul_f32_e32 v80, v17, v17
	v_mul_f32_e32 v81, v21, v21
	v_mul_f32_e32 v82, v25, v25
	v_mul_f32_e32 v83, v29, v29
	v_fmac_f32_e32 v80, v16, v16
	v_fmac_f32_e32 v81, v20, v20
	v_fmac_f32_e32 v82, v24, v24
	v_fmac_f32_e32 v83, v28, v28
	v_fmac_f32_e32 v80, v18, v18
	v_fmac_f32_e32 v81, v22, v22
	v_fmac_f32_e32 v82, v26, v26
	v_fmac_f32_e32 v83, v30, v30
	v_fmac_f32_e32 v80, v19, v19
	v_fmac_f32_e32 v81, v23, v23
	v_fmac_f32_e32 v82, v27, v27
	v_fmac_f32_e32 v83, v31, v31
	v_add_f32_e32 v84, v80, v81
	v_add_f32_e32 v84, v84, v82
	v_add_f32_e32 v84, v84, v83
	ds_bpermute_b32 v85, v98, v84
	s_waitcnt lgkmcnt(0)
	v_add_f32_e32 v84, v84, v85
	ds_bpermute_b32 v85, v99, v84
	s_waitcnt lgkmcnt(0)
	v_add_f32_e32 v84, v84, v85
	ds_bpermute_b32 v85, v100, v84
	s_waitcnt lgkmcnt(0)
	v_add_f32_e32 v84, v84, v85
	ds_bpermute_b32 v85, v101, v84
	s_waitcnt lgkmcnt(0)
	v_add_f32_e32 v84, v84, v85
	ds_bpermute_b32 v85, v102, v84
	s_waitcnt lgkmcnt(0)
	v_add_f32_e32 v84, v84, v85
	ds_bpermute_b32 v85, v103, v84
	s_waitcnt lgkmcnt(0)
	v_add_f32_e32 v84, v84, v85
	v_fmamk_f32 v84, v84, 0x3a800000, v104
	v_mul_f32_e32 v85, 0x4b800000, v84
	v_cmp_gt_f32_e32 vcc, 0x800000, v84
	s_nop 1
	v_cndmask_b32_e32 v84, v84, v85, vcc
	v_rsq_f32_e32 v84, v84
	s_nop 0
	v_mul_f32_e32 v85, 0x45800000, v84
	v_cndmask_b32_e32 v106, v84, v85, vcc
	s_lshl_b32 s99, s98, 12
	s_add_u32 s100, s88, s99
	s_addc_u32 s101, s89, 0
	v_pk_mul_f32 v[16:17], v[16:17], v[106:107] op_sel_hi:[1,0]
	v_pk_mul_f32 v[18:19], v[18:19], v[106:107] op_sel_hi:[1,0]
	v_pk_mul_f32 v[16:17], v[32:33], v[16:17]
	v_pk_mul_f32 v[18:19], v[34:35], v[18:19]
	global_store_dwordx4 v96, v[16:19], s[100:101] offset:0
	v_pk_mul_f32 v[20:21], v[20:21], v[106:107] op_sel_hi:[1,0]
	v_pk_mul_f32 v[22:23], v[22:23], v[106:107] op_sel_hi:[1,0]
	v_pk_mul_f32 v[20:21], v[36:37], v[20:21]
	v_pk_mul_f32 v[22:23], v[38:39], v[22:23]
	global_store_dwordx4 v96, v[20:23], s[100:101] offset:1024
	v_pk_mul_f32 v[24:25], v[24:25], v[106:107] op_sel_hi:[1,0]
	v_pk_mul_f32 v[26:27], v[26:27], v[106:107] op_sel_hi:[1,0]
	v_pk_mul_f32 v[24:25], v[40:41], v[24:25]
	v_pk_mul_f32 v[26:27], v[42:43], v[26:27]
	global_store_dwordx4 v96, v[24:27], s[100:101] offset:2048
	v_pk_mul_f32 v[28:29], v[28:29], v[106:107] op_sel_hi:[1,0]
	v_pk_mul_f32 v[30:31], v[30:31], v[106:107] op_sel_hi:[1,0]
	v_pk_mul_f32 v[28:29], v[44:45], v[28:29]
	v_pk_mul_f32 v[30:31], v[46:47], v[30:31]
	global_store_dwordx4 v96, v[28:31], s[100:101] offset:3072
	s_add_u32 s98, s98, 0x800
	s_add_u32 s98, s98, 0x800
	s_lshl_b32 s99, s98, 12
	s_add_u32 s100, s88, s99
	s_addc_u32 s101, s89, 0
	global_load_dwordx4 v[16:19], v96, s[100:101] offset:0
	global_load_dwordx4 v[20:23], v96, s[100:101] offset:1024
	global_load_dwordx4 v[24:27], v96, s[100:101] offset:2048
	global_load_dwordx4 v[28:31], v96, s[100:101] offset:3072
	s_sub_u32 s98, s98, 0x800
	s_waitcnt vmcnt(8)
	v_mul_f32_e32 v80, v1, v1
	v_mul_f32_e32 v81, v5, v5
	v_mul_f32_e32 v82, v9, v9
	v_mul_f32_e32 v83, v13, v13
	v_fmac_f32_e32 v80, v0, v0
	v_fmac_f32_e32 v81, v4, v4
	v_fmac_f32_e32 v82, v8, v8
	v_fmac_f32_e32 v83, v12, v12
	v_fmac_f32_e32 v80, v2, v2
	v_fmac_f32_e32 v81, v6, v6
	v_fmac_f32_e32 v82, v10, v10
	v_fmac_f32_e32 v83, v14, v14
	v_fmac_f32_e32 v80, v3, v3
	v_fmac_f32_e32 v81, v7, v7
	v_fmac_f32_e32 v82, v11, v11
	v_fmac_f32_e32 v83, v15, v15
	v_add_f32_e32 v84, v80, v81
	v_add_f32_e32 v84, v84, v82
	v_add_f32_e32 v84, v84, v83
	ds_bpermute_b32 v85, v98, v84
	s_waitcnt lgkmcnt(0)
	v_add_f32_e32 v84, v84, v85
	ds_bpermute_b32 v85, v99, v84
	s_waitcnt lgkmcnt(0)
	v_add_f32_e32 v84, v84, v85
	ds_bpermute_b32 v85, v100, v84
	s_waitcnt lgkmcnt(0)
	v_add_f32_e32 v84, v84, v85
	ds_bpermute_b32 v85, v101, v84
	s_waitcnt lgkmcnt(0)
	v_add_f32_e32 v84, v84, v85
	ds_bpermute_b32 v85, v102, v84
	s_waitcnt lgkmcnt(0)
	v_add_f32_e32 v84, v84, v85
	ds_bpermute_b32 v85, v103, v84
	s_waitcnt lgkmcnt(0)
	v_add_f32_e32 v84, v84, v85
	v_fmamk_f32 v84, v84, 0x3a800000, v104
	v_mul_f32_e32 v85, 0x4b800000, v84
	v_cmp_gt_f32_e32 vcc, 0x800000, v84
	s_nop 1
	v_cndmask_b32_e32 v84, v84, v85, vcc
	v_rsq_f32_e32 v84, v84
	s_nop 0
	v_mul_f32_e32 v85, 0x45800000, v84
	v_cndmask_b32_e32 v106, v84, v85, vcc
	s_lshl_b32 s99, s98, 12
	s_add_u32 s100, s88, s99
	s_addc_u32 s101, s89, 0
	v_pk_mul_f32 v[0:1], v[0:1], v[106:107] op_sel_hi:[1,0]
	v_pk_mul_f32 v[2:3], v[2:3], v[106:107] op_sel_hi:[1,0]
	v_pk_mul_f32 v[0:1], v[32:33], v[0:1]
	v_pk_mul_f32 v[2:3], v[34:35], v[2:3]
	global_store_dwordx4 v96, v[0:3], s[100:101] offset:0
	v_pk_mul_f32 v[4:5], v[4:5], v[106:107] op_sel_hi:[1,0]
	v_pk_mul_f32 v[6:7], v[6:7], v[106:107] op_sel_hi:[1,0]
	v_pk_mul_f32 v[4:5], v[36:37], v[4:5]
	v_pk_mul_f32 v[6:7], v[38:39], v[6:7]
	global_store_dwordx4 v96, v[4:7], s[100:101] offset:1024
	v_pk_mul_f32 v[8:9], v[8:9], v[106:107] op_sel_hi:[1,0]
	v_pk_mul_f32 v[10:11], v[10:11], v[106:107] op_sel_hi:[1,0]
	v_pk_mul_f32 v[8:9], v[40:41], v[8:9]
	v_pk_mul_f32 v[10:11], v[42:43], v[10:11]
	global_store_dwordx4 v96, v[8:11], s[100:101] offset:2048
	v_pk_mul_f32 v[12:13], v[12:13], v[106:107] op_sel_hi:[1,0]
	v_pk_mul_f32 v[14:15], v[14:15], v[106:107] op_sel_hi:[1,0]
	v_pk_mul_f32 v[12:13], v[44:45], v[12:13]
	v_pk_mul_f32 v[14:15], v[46:47], v[14:15]
	global_store_dwordx4 v96, v[12:15], s[100:101] offset:3072
	s_add_u32 s98, s98, 0x800
	s_waitcnt vmcnt(4)
	v_mul_f32_e32 v80, v17, v17
	v_mul_f32_e32 v81, v21, v21
	v_mul_f32_e32 v82, v25, v25
	v_mul_f32_e32 v83, v29, v29
	v_fmac_f32_e32 v80, v16, v16
	v_fmac_f32_e32 v81, v20, v20
	v_fmac_f32_e32 v82, v24, v24
	v_fmac_f32_e32 v83, v28, v28
	v_fmac_f32_e32 v80, v18, v18
	v_fmac_f32_e32 v81, v22, v22
	v_fmac_f32_e32 v82, v26, v26
	v_fmac_f32_e32 v83, v30, v30
	v_fmac_f32_e32 v80, v19, v19
	v_fmac_f32_e32 v81, v23, v23
	v_fmac_f32_e32 v82, v27, v27
	v_fmac_f32_e32 v83, v31, v31
	v_add_f32_e32 v84, v80, v81
	v_add_f32_e32 v84, v84, v82
	v_add_f32_e32 v84, v84, v83
	ds_bpermute_b32 v85, v98, v84
	s_waitcnt lgkmcnt(0)
	v_add_f32_e32 v84, v84, v85
	ds_bpermute_b32 v85, v99, v84
	s_waitcnt lgkmcnt(0)
	v_add_f32_e32 v84, v84, v85
	ds_bpermute_b32 v85, v100, v84
	s_waitcnt lgkmcnt(0)
	v_add_f32_e32 v84, v84, v85
	ds_bpermute_b32 v85, v101, v84
	s_waitcnt lgkmcnt(0)
	v_add_f32_e32 v84, v84, v85
	ds_bpermute_b32 v85, v102, v84
	s_waitcnt lgkmcnt(0)
	v_add_f32_e32 v84, v84, v85
	ds_bpermute_b32 v85, v103, v84
	s_waitcnt lgkmcnt(0)
	v_add_f32_e32 v84, v84, v85
	v_fmamk_f32 v84, v84, 0x3a800000, v104
	v_mul_f32_e32 v85, 0x4b800000, v84
	v_cmp_gt_f32_e32 vcc, 0x800000, v84
	s_nop 1
	v_cndmask_b32_e32 v84, v84, v85, vcc
	v_rsq_f32_e32 v84, v84
	s_nop 0
	v_mul_f32_e32 v85, 0x45800000, v84
	v_cndmask_b32_e32 v106, v84, v85, vcc
	s_lshl_b32 s99, s98, 12
	s_add_u32 s100, s88, s99
	s_addc_u32 s101, s89, 0
	v_pk_mul_f32 v[16:17], v[16:17], v[106:107] op_sel_hi:[1,0]
	v_pk_mul_f32 v[18:19], v[18:19], v[106:107] op_sel_hi:[1,0]
	v_pk_mul_f32 v[16:17], v[32:33], v[16:17]
	v_pk_mul_f32 v[18:19], v[34:35], v[18:19]
	global_store_dwordx4 v96, v[16:19], s[100:101] offset:0
	v_pk_mul_f32 v[20:21], v[20:21], v[106:107] op_sel_hi:[1,0]
	v_pk_mul_f32 v[22:23], v[22:23], v[106:107] op_sel_hi:[1,0]
	v_pk_mul_f32 v[20:21], v[36:37], v[20:21]
	v_pk_mul_f32 v[22:23], v[38:39], v[22:23]
	global_store_dwordx4 v96, v[20:23], s[100:101] offset:1024
	v_pk_mul_f32 v[24:25], v[24:25], v[106:107] op_sel_hi:[1,0]
	v_pk_mul_f32 v[26:27], v[26:27], v[106:107] op_sel_hi:[1,0]
	v_pk_mul_f32 v[24:25], v[40:41], v[24:25]
	v_pk_mul_f32 v[26:27], v[42:43], v[26:27]
	global_store_dwordx4 v96, v[24:27], s[100:101] offset:2048
	v_pk_mul_f32 v[28:29], v[28:29], v[106:107] op_sel_hi:[1,0]
	v_pk_mul_f32 v[30:31], v[30:31], v[106:107] op_sel_hi:[1,0]
	v_pk_mul_f32 v[28:29], v[44:45], v[28:29]
	v_pk_mul_f32 v[30:31], v[46:47], v[30:31]
	global_store_dwordx4 v96, v[28:31], s[100:101] offset:3072
